# diff loop: rescale-flag check moved off the producer critical path, on top of v58
# speedup vs baseline: 1.0001x; 1.0001x over previous
; #define SBAR() __builtin_amdgcn_sched_barrier(0)
; __device__ __forceinline__ int crow(int r, int hi) { return (r & 3) + 8 * (r >> 2) + 4 * hi; }
; __device__ __forceinline__ void partialSM(f32x16& p0, f32x16& p1, float& m_reg, float& mn, float& alpha, const float C, const float thr_raw) {
;   float pmax = p0[0];
; #pragma unroll
;   for (int r = 1; r < 16; ++r) pmax = fmaxf(pmax, p0[r]);
; #pragma unroll
;   for (int r = 0; r < 16; ++r) pmax = fmaxf(pmax, p1[r]);
;   { auto rr = __builtin_amdgcn_permlane32_swap(__float_as_uint(pmax), __float_as_uint(pmax), false, false);
;     pmax = fmaxf(__uint_as_float(rr[0]), __uint_as_float(rr[1])); }
;   if (__builtin_expect(__all(pmax - m_reg <= thr_raw), 1)) { mn = m_reg; alpha = 1.f; }
;   else { mn = fmaxf(m_reg, pmax); alpha = __builtin_amdgcn_exp2f((m_reg - mn) * C); m_reg = mn; }
;   const float mnC = -mn * C;
; #pragma unroll
;   for (int r = 0; r < 16; ++r) p0[r] = fmaf(p0[r], C, mnC);
; #pragma unroll
;   for (int r = 0; r < 16; ++r) p1[r] = fmaf(p1[r], C, mnC);
; #pragma unroll
;   for (int r = 0; r < 16; ++r) p0[r] = __builtin_amdgcn_exp2f(p0[r]);
; }
; __device__ __forceinline__ void attn_core_pair(f32x16 (&o)[4], const bf16_t* __restrict__ Qb, const bf16_t* __restrict__ Kh, const bf16_t* __restrict__ Vh, const int seq, const float C, const float thr_raw, char* lds) {
;     ...
;     if (j >= 1) {
;       const int pp = (j - 1) & 1;
;       if (__builtin_amdgcn_readfirstlane(fl_l[pp * 4 + rb]) != 0u) {
;         const float* al = ma + 256 + pp * 128 + rb * 32;
; #pragma unroll
;         for (int d = 0; d < 4; ++d)
; #pragma unroll
;           for (int r = 0; r < 16; ++r) o[d][r] *= al[crow(r, hi)]; }
;       if (role != pp) { pa0 = *(const bf16x8*)(P_l); pa1 = *(const bf16x8*)(P_l + 1024); pa2 = *(const bf16x8*)(P_l + 2048); pa3 = *(const bf16x8*)(P_l + 3072); }
;       pv_d0(o, vb0 + vprev * (2 * SHM_V), pa0, pa1, pa2, pa3);
;     }
;     if (j < NT && role == par) {
;       float m_reg = (j == 0) ? -1e30f : m_l[r32], l_reg = (j == 0) ? 0.f : l_l[r32], mn, al;
;       SBAR(); qkt<8, 8>(p0, p1, K_lds + kb * SHM_K, nullptr, qr, nullptr, r32, hi);
;       partialSM(p0, p1, m_reg, mn, al, C, thr_raw);
;       finishSM(p0, p1, al, l_reg, pa0, pa1, pa2, pa3); SBAR();
.LBB0_381:
	s_and_b32 s57, s40, 1
	s_xor_b32 s30, s57, 1
	s_mov_b32 s99, s30
	v_cmp_ne_u32_e32 vcc, s30, v157
	s_and_saveexec_b64 s[30:31], vcc
	s_cbranch_execz .Ldiff_cons
	ds_read_b128 v[240:243], v225
	ds_read_b128 v[244:247], v225 offset:1024
	ds_read_b128 v[248:251], v225 offset:2048
	ds_read_b128 v[252:255], v225 offset:3072
	ds_read_b32 v163, v203
	ds_read_b32 v169, v201
	v_add_u32_e32 v68, v205, v155
	ds_read_b128 v[64:67], v68
	ds_read_b128 v[68:71], v68 offset:8192
	v_add_u32_e32 v171, v206, v155
	ds_read_b128 v[228:231], v171
	ds_read_b128 v[232:235], v171 offset:8192
	v_add_u32_e32 v171, v207, v155
	s_waitcnt lgkmcnt(3)
	v_mfma_f32_32x32x16_bf16 v[80:95], v[64:67], v[124:127], 0
	s_waitcnt lgkmcnt(2)
	v_mfma_f32_32x32x16_bf16 v[64:79], v[68:71], v[124:127], 0
	s_waitcnt lgkmcnt(1)
	v_mfma_f32_32x32x16_bf16 v[80:95], v[228:231], v[120:123], v[80:95]
	s_waitcnt lgkmcnt(0)
	v_mfma_f32_32x32x16_bf16 v[64:79], v[232:235], v[120:123], v[64:79]
	ds_read_b128 v[228:231], v171
	ds_read_b128 v[232:235], v171 offset:8192
	v_add_u32_e32 v171, v208, v155
	s_waitcnt lgkmcnt(1)
	v_mfma_f32_32x32x16_bf16 v[80:95], v[228:231], v[116:119], v[80:95]
	s_waitcnt lgkmcnt(0)
	v_mfma_f32_32x32x16_bf16 v[64:79], v[232:235], v[116:119], v[64:79]
	ds_read_b128 v[228:231], v171
	ds_read_b128 v[232:235], v171 offset:8192
	v_add_u32_e32 v171, v209, v155
	s_waitcnt lgkmcnt(1)
	v_mfma_f32_32x32x16_bf16 v[80:95], v[228:231], v[112:115], v[80:95]
	s_waitcnt lgkmcnt(0)
	v_mfma_f32_32x32x16_bf16 v[64:79], v[232:235], v[112:115], v[64:79]
	ds_read_b128 v[228:231], v171
	ds_read_b128 v[232:235], v171 offset:8192
	v_add_u32_e32 v171, v210, v155
	s_waitcnt lgkmcnt(1)
	v_mfma_f32_32x32x16_bf16 v[80:95], v[228:231], v[108:111], v[80:95]
	s_waitcnt lgkmcnt(0)
	v_mfma_f32_32x32x16_bf16 v[64:79], v[232:235], v[108:111], v[64:79]
	ds_read_b128 v[228:231], v171
	ds_read_b128 v[232:235], v171 offset:8192
	v_add_u32_e32 v171, v211, v155
	s_waitcnt lgkmcnt(1)
	v_mfma_f32_32x32x16_bf16 v[80:95], v[228:231], v[104:107], v[80:95]
	s_waitcnt lgkmcnt(0)
	v_mfma_f32_32x32x16_bf16 v[64:79], v[232:235], v[104:107], v[64:79]
	ds_read_b128 v[228:231], v171
	ds_read_b128 v[232:235], v171 offset:8192
	v_add_u32_e32 v171, v212, v155
	s_waitcnt lgkmcnt(1)
	v_mfma_f32_32x32x16_bf16 v[80:95], v[228:231], v[100:103], v[80:95]
	ds_read_b128 v[228:231], v171
	ds_read_b128 v[236:239], v171 offset:8192
	s_waitcnt lgkmcnt(1)
	v_mfma_f32_32x32x16_bf16 v[80:95], v[228:231], v[96:99], v[80:95]
	v_mfma_f32_32x32x16_bf16 v[64:79], v[232:235], v[100:103], v[64:79]
	s_nop 10
	v_max_f32_e32 v171, v81, v81
	v_max_f32_e32 v173, v80, v80
	v_max_f32_e32 v171, v173, v171
	v_max3_f32 v171, v171, v82, v83
	v_max3_f32 v171, v171, v84, v85
	v_max3_f32 v171, v171, v86, v87
	v_max3_f32 v171, v171, v88, v89
	s_waitcnt lgkmcnt(0)
	v_mfma_f32_32x32x16_bf16 v[64:79], v[236:239], v[96:99], v[64:79]
	v_max3_f32 v171, v171, v90, v91
	v_max3_f32 v171, v171, v92, v93
	v_max3_f32 v171, v171, v94, v95
	s_nop 8
	v_max3_f32 v171, v171, v64, v65
	v_max3_f32 v171, v171, v66, v67
	v_max3_f32 v171, v171, v68, v69
	v_max3_f32 v171, v171, v70, v71
	v_max3_f32 v171, v171, v72, v73
	v_max3_f32 v171, v171, v74, v75
	v_max3_f32 v171, v171, v76, v77
	v_max3_f32 v171, v171, v78, v79
	v_mov_b32_e32 v173, v171
	s_nop 1
	v_permlane32_swap_b32_e32 v171, v173
	v_max_f32_e32 v173, v173, v173
	v_max_f32_e32 v171, v171, v171
	v_max_f32_e32 v171, v171, v173
	v_sub_f32_e32 v173, v171, v169
	v_cmp_ge_f32_e32 vcc, s47, v173
	v_max_f32_e32 v173, v169, v169
	v_max_f32_e32 v171, v173, v171
	v_sub_f32_e32 v173, v169, v171
	v_mul_f32_e32 v173, 0x3e0293ee, v173
	v_exp_f32_e32 v173, v173
	s_cmp_eq_u64 vcc, exec
	s_cselect_b64 vcc, -1, 0
	v_cndmask_b32_e32 v171, v171, v169, vcc
	v_cndmask_b32_e64 v169, v173, 1.0, vcc
	v_mul_f32_e32 v173, 0xbe0293ee, v171
	v_fmamk_f32 v80, v80, 0x3e0293ee, v173
	v_fmamk_f32 v81, v81, 0x3e0293ee, v173
	v_fmamk_f32 v82, v82, 0x3e0293ee, v173
	v_fmamk_f32 v83, v83, 0x3e0293ee, v173
	v_fmamk_f32 v84, v84, 0x3e0293ee, v173
	v_fmamk_f32 v85, v85, 0x3e0293ee, v173
	v_fmamk_f32 v86, v86, 0x3e0293ee, v173
	v_fmamk_f32 v87, v87, 0x3e0293ee, v173
	v_fmamk_f32 v88, v88, 0x3e0293ee, v173
	v_fmamk_f32 v89, v89, 0x3e0293ee, v173
	v_fmamk_f32 v90, v90, 0x3e0293ee, v173
	v_fmamk_f32 v91, v91, 0x3e0293ee, v173
	v_fmamk_f32 v92, v92, 0x3e0293ee, v173
	v_fmamk_f32 v93, v93, 0x3e0293ee, v173
	v_fmamk_f32 v94, v94, 0x3e0293ee, v173
	v_fmamk_f32 v95, v95, 0x3e0293ee, v173
	v_fmamk_f32 v64, v64, 0x3e0293ee, v173
	v_fmamk_f32 v65, v65, 0x3e0293ee, v173
	v_fmamk_f32 v66, v66, 0x3e0293ee, v173
	v_fmamk_f32 v67, v67, 0x3e0293ee, v173
	v_fmamk_f32 v68, v68, 0x3e0293ee, v173
	v_fmamk_f32 v69, v69, 0x3e0293ee, v173
	v_fmamk_f32 v70, v70, 0x3e0293ee, v173
	v_fmamk_f32 v71, v71, 0x3e0293ee, v173
	v_fmamk_f32 v72, v72, 0x3e0293ee, v173
	v_fmamk_f32 v73, v73, 0x3e0293ee, v173
	v_fmamk_f32 v74, v74, 0x3e0293ee, v173
	v_fmamk_f32 v75, v75, 0x3e0293ee, v173
	v_fmamk_f32 v76, v76, 0x3e0293ee, v173
	v_fmamk_f32 v77, v77, 0x3e0293ee, v173
	v_fmamk_f32 v78, v78, 0x3e0293ee, v173
	v_fmac_f32_e32 v173, 0x3e0293ee, v79
	v_exp_f32_e32 v79, v80
	v_exp_f32_e32 v175, v81
	v_exp_f32_e32 v82, v82
	v_exp_f32_e32 v83, v83
	v_exp_f32_e32 v84, v84
	v_exp_f32_e32 v183, v64
	v_add_f32_e32 v64, 0, v79
	v_exp_f32_e32 v85, v85
	v_add_f32_e32 v64, v175, v64
	v_exp_f32_e32 v86, v86
	v_add_f32_e32 v64, v82, v64
	v_exp_f32_e32 v87, v87
	v_add_f32_e32 v64, v83, v64
	v_exp_f32_e32 v88, v88
	v_add_f32_e32 v64, v84, v64
	v_exp_f32_e32 v89, v89
	v_add_f32_e32 v64, v85, v64
	v_exp_f32_e32 v90, v90
	v_add_f32_e32 v64, v86, v64
	v_exp_f32_e32 v91, v91
	v_add_f32_e32 v64, v87, v64
	v_exp_f32_e32 v92, v92
; #define SBAR() __builtin_amdgcn_sched_barrier(0)
; __device__ __forceinline__ int crow(int r, int hi) { return (r & 3) + 8 * (r >> 2) + 4 * hi; }
; __device__ __forceinline__ void attn_core_pair(f32x16 (&o)[4], const bf16_t* __restrict__ Qb, const bf16_t* __restrict__ Kh, const bf16_t* __restrict__ Vh, const int seq, const float C, const float thr_raw, char* lds) {
;     ...
;       if (__builtin_amdgcn_readfirstlane(fl_l[pp * 4 + rb]) != 0u) {
;         const float* al = ma + 256 + pp * 128 + rb * 32;
; #pragma unroll
;         for (int d = 0; d < 4; ++d)
; #pragma unroll
;           for (int r = 0; r < 16; ++r) o[d][r] *= al[crow(r, hi)]; }
;     ...
;       finishSM(p0, p1, al, l_reg, pa0, pa1, pa2, pa3); SBAR();
;       *(bf16x8*)(P_l) = pa0; *(bf16x8*)(P_l + 1024) = pa1; *(bf16x8*)(P_l + 2048) = pa2; *(bf16x8*)(P_l + 3072) = pa3;
;       const bool anyr = __any(al < 1.f);
;       if (hi == 0) { m_l[r32] = m_reg; l_l[r32] = l_reg; ma[256 + par * 128 + rb * 32 + r32] = al; }
;       if (lane == 0) fl_l[par * 4 + rb] = anyr ? 1u : 0u;
	v_add_f32_e32 v64, v88, v64
	v_exp_f32_e32 v93, v93
	v_add_f32_e32 v64, v89, v64
	v_exp_f32_e32 v94, v94
	v_add_f32_e32 v64, v90, v64
	v_exp_f32_e32 v95, v95
	v_add_f32_e32 v64, v91, v64
	v_add_f32_e32 v64, v92, v64
	v_exp_f32_e32 v185, v65
	v_add_f32_e32 v64, v93, v64
	v_exp_f32_e32 v227, v66
	v_add_f32_e32 v64, v94, v64
	v_exp_f32_e32 v228, v67
	v_add_f32_e32 v64, v95, v64
	v_exp_f32_e32 v229, v68
	v_add_f32_e32 v64, v183, v64
	v_exp_f32_e32 v230, v69
	v_add_f32_e32 v64, v185, v64
	v_exp_f32_e32 v231, v70
	v_add_f32_e32 v64, v227, v64
	v_exp_f32_e32 v232, v71
	v_add_f32_e32 v64, v228, v64
	v_exp_f32_e32 v72, v72
	v_add_f32_e32 v64, v229, v64
	v_exp_f32_e32 v73, v73
	v_add_f32_e32 v64, v230, v64
	v_exp_f32_e32 v74, v74
	v_add_f32_e32 v64, v231, v64
	v_exp_f32_e32 v75, v75
	v_add_f32_e32 v64, v232, v64
	v_exp_f32_e32 v233, v76
	v_add_f32_e32 v64, v72, v64
	v_exp_f32_e32 v234, v77
	v_add_f32_e32 v64, v73, v64
	v_exp_f32_e32 v235, v78
	v_add_f32_e32 v64, v74, v64
	v_exp_f32_e32 v173, v173
	v_add_f32_e32 v64, v75, v64
	v_add_f32_e32 v64, v233, v64
	v_add_f32_e32 v64, v234, v64
	v_add_f32_e32 v64, v235, v64
	v_add_f32_e32 v80, v173, v64
	v_mov_b32_e32 v81, v80
	v_cvt_pk_bf16_f32 v64, v79, v175
	v_cvt_pk_bf16_f32 v65, v82, v83
	v_cvt_pk_bf16_f32 v66, v84, v85
	v_cvt_pk_bf16_f32 v67, v86, v87
	v_cvt_pk_bf16_f32 v68, v88, v89
	v_cvt_pk_bf16_f32 v69, v90, v91
	v_cvt_pk_bf16_f32 v70, v92, v93
	v_cvt_pk_bf16_f32 v71, v94, v95
	v_cvt_pk_bf16_f32 v76, v183, v185
	v_cvt_pk_bf16_f32 v77, v227, v228
	v_cvt_pk_bf16_f32 v78, v229, v230
	v_cvt_pk_bf16_f32 v79, v231, v232
	v_cvt_pk_bf16_f32 v72, v72, v73
	v_cvt_pk_bf16_f32 v73, v74, v75
	v_cvt_pk_bf16_f32 v74, v233, v234
	v_cvt_pk_bf16_f32 v75, v235, v173
	s_nop 1
	v_permlane32_swap_b32_e32 v80, v81
	v_permlane32_swap_b32_e32 v64, v66
	v_permlane32_swap_b32_e32 v65, v67
	v_permlane32_swap_b32_e32 v68, v70
	v_permlane32_swap_b32_e32 v69, v71
	v_permlane32_swap_b32_e32 v76, v78
	v_permlane32_swap_b32_e32 v77, v79
	v_permlane32_swap_b32_e32 v72, v74
	v_permlane32_swap_b32_e32 v73, v75
	v_lshl_add_u32 v82, s99, 4, v200
	ds_read_b32 v82, v82
	v_cmp_gt_f32_e32 vcc, 1.0, v169
	ds_write_b128 v225, v[64:67]
	ds_write_b128 v225, v[68:71] offset:1024
	ds_write_b128 v225, v[76:79] offset:2048
	ds_write_b128 v225, v[72:75] offset:3072
	s_and_saveexec_b64 s[38:39], s[2:3]
	s_cbranch_execz .LBB0_388
	v_add_f32_e32 v80, v80, v81
	v_fmac_f32_e32 v80, v163, v169
	ds_write_b32 v201, v171
	ds_write_b32 v203, v80
	v_add_u32_e32 v80, v201, v213
	ds_write_b32 v80, v169 offset:1024
.LBB0_388:
	s_or_b64 exec, exec, s[38:39]
	s_and_saveexec_b64 s[38:39], s[4:5]
	s_cmp_lg_u64 vcc, 0
	s_cselect_b64 s[58:59], -1, 0
	v_cndmask_b32_e64 v80, 0, 1, s[58:59]
	v_add_u32_e32 v81, v200, v214
	ds_write_b32 v81, v80
	s_or_b64 exec, exec, s[38:39]
	s_waitcnt lgkmcnt(0)
	v_readfirstlane_b32 s98, v82
	s_cmp_eq_u32 s98, 0
	s_cbranch_scc1 .Ldiff_p_nors
	v_lshl_add_u32 v92, s99, 9, v215
	ds_read_b128 v[80:83], v92 offset:96
	ds_read_b128 v[84:87], v92 offset:64
	ds_read_b128 v[88:91], v92 offset:32
	ds_read_b128 v[92:95], v92
	s_waitcnt lgkmcnt(3)
	v_pk_mul_f32 v[62:63], v[62:63], v[82:83]
	s_waitcnt lgkmcnt(2)
	v_pk_mul_f32 v[58:59], v[58:59], v[86:87]
	s_waitcnt lgkmcnt(1)
	v_pk_mul_f32 v[54:55], v[54:55], v[90:91]
	s_waitcnt lgkmcnt(0)
	v_pk_mul_f32 v[50:51], v[50:51], v[94:95]
	v_pk_mul_f32 v[60:61], v[60:61], v[80:81]
	v_pk_mul_f32 v[56:57], v[56:57], v[84:85]
	v_pk_mul_f32 v[52:53], v[52:53], v[88:89]
	v_pk_mul_f32 v[48:49], v[48:49], v[92:93]
	v_pk_mul_f32 v[46:47], v[82:83], v[46:47]
	v_pk_mul_f32 v[42:43], v[86:87], v[42:43]
	v_pk_mul_f32 v[38:39], v[90:91], v[38:39]
	v_pk_mul_f32 v[34:35], v[94:95], v[34:35]
	v_pk_mul_f32 v[44:45], v[80:81], v[44:45]
	v_pk_mul_f32 v[40:41], v[84:85], v[40:41]
	v_pk_mul_f32 v[36:37], v[88:89], v[36:37]
	v_pk_mul_f32 v[32:33], v[92:93], v[32:33]
	v_pk_mul_f32 v[30:31], v[82:83], v[30:31]
	v_pk_mul_f32 v[26:27], v[86:87], v[26:27]
	v_pk_mul_f32 v[22:23], v[90:91], v[22:23]
	v_pk_mul_f32 v[18:19], v[94:95], v[18:19]
	v_pk_mul_f32 v[28:29], v[80:81], v[28:29]
	v_pk_mul_f32 v[24:25], v[84:85], v[24:25]
	v_pk_mul_f32 v[20:21], v[88:89], v[20:21]
	v_pk_mul_f32 v[16:17], v[92:93], v[16:17]
	v_pk_mul_f32 v[14:15], v[82:83], v[14:15]
	v_pk_mul_f32 v[10:11], v[86:87], v[10:11]
	v_pk_mul_f32 v[6:7], v[90:91], v[6:7]
	v_pk_mul_f32 v[2:3], v[94:95], v[2:3]
	v_pk_mul_f32 v[12:13], v[80:81], v[12:13]
	v_pk_mul_f32 v[8:9], v[84:85], v[8:9]
	v_pk_mul_f32 v[4:5], v[88:89], v[4:5]
	v_pk_mul_f32 v[0:1], v[92:93], v[0:1]
; #define SBAR() __builtin_amdgcn_sched_barrier(0)
; template <int D0> __device__ __forceinline__ void pv_one(f32x16& od, int vb, bf16x8 pa0, bf16x8 pa1, bf16x8 pa2, bf16x8 pa3) {
;   const s16x4 l0 = tr_read<v_rd_off(D0, 0, 0)>(vb), h0 = tr_read<v_rd_off(D0, 0, 1)>(vb), l1 = tr_read<v_rd_off(D0, 1, 0)>(vb), h1 = tr_read<v_rd_off(D0, 1, 1)>(vb);
;   const s16x4 l2 = tr_read<v_rd_off(D0, 2, 0)>(vb), h2 = tr_read<v_rd_off(D0, 2, 1)>(vb), l3 = tr_read<v_rd_off(D0, 3, 0)>(vb), h3 = tr_read<v_rd_off(D0, 3, 1)>(vb);
;   asm volatile("s_waitcnt lgkmcnt(0)" ::: "memory"); SBAR();
;     ...
;   od = __builtin_amdgcn_mfma_f32_32x32x16_bf16(pa0, PK(l0, h0), od, 0, 0, 0);
;   od = __builtin_amdgcn_mfma_f32_32x32x16_bf16(pa1, PK(l1, h1), od, 0, 0, 0);
;   od = __builtin_amdgcn_mfma_f32_32x32x16_bf16(pa2, PK(l2, h2), od, 0, 0, 0);
;   od = __builtin_amdgcn_mfma_f32_32x32x16_bf16(pa3, PK(l3, h3), od, 0, 0, 0);
;     ...
; }
; __device__ __forceinline__ void pv_d0(f32x16* o, int vb, bf16x8 pa0, bf16x8 pa1, bf16x8 pa2, bf16x8 pa3) {
;   pv_one<0>(o[0], vb, pa0, pa1, pa2, pa3); pv_one<1>(o[1], vb, pa0, pa1, pa2, pa3); pv_one<2>(o[2], vb, pa0, pa1, pa2, pa3); pv_one<3>(o[3], vb, pa0, pa1, pa2, pa3);
; __device__ __forceinline__ void attn_core_pair(f32x16 (&o)[4], const bf16_t* __restrict__ Qb, const bf16_t* __restrict__ Kh, const bf16_t* __restrict__ Vh, const int seq, const float C, const float thr_raw, char* lds) {
;     ...
;       pv_d0(o, vb0 + vprev * (2 * SHM_V), pa0, pa1, pa2, pa3);
.Ldiff_p_nors:
	v_lshl_add_u32 v163, s16, 15, v204
	ds_read_b64_tr_b16 v[80:81], v163 offset:0
	ds_read_b64_tr_b16 v[82:83], v163 offset:0x800
	ds_read_b64_tr_b16 v[84:85], v163 offset:0x1000
	ds_read_b64_tr_b16 v[86:87], v163 offset:0x1800
	ds_read_b64_tr_b16 v[88:89], v163 offset:0x2000
	ds_read_b64_tr_b16 v[90:91], v163 offset:0x2800
	ds_read_b64_tr_b16 v[92:93], v163 offset:0x3000
	ds_read_b64_tr_b16 v[94:95], v163 offset:0x3800
	s_waitcnt lgkmcnt(6)
	v_mfma_f32_32x32x16_bf16 v[48:63], v[240:243], v[80:83], v[48:63]
	ds_read_b64_tr_b16 v[80:81], v163 offset:0x200
	ds_read_b64_tr_b16 v[82:83], v163 offset:0xa00
	s_waitcnt lgkmcnt(6)
	v_mfma_f32_32x32x16_bf16 v[48:63], v[244:247], v[84:87], v[48:63]
	ds_read_b64_tr_b16 v[84:85], v163 offset:0x1200
	ds_read_b64_tr_b16 v[86:87], v163 offset:0x1a00
	s_waitcnt lgkmcnt(6)
	v_mfma_f32_32x32x16_bf16 v[48:63], v[248:251], v[88:91], v[48:63]
	ds_read_b64_tr_b16 v[88:89], v163 offset:0x2200
	ds_read_b64_tr_b16 v[90:91], v163 offset:0x2a00
	ds_read_b64_tr_b16 v[228:229], v163 offset:0x3200
	ds_read_b64_tr_b16 v[230:231], v163 offset:0x3a00
	s_waitcnt lgkmcnt(8)
	v_mfma_f32_32x32x16_bf16 v[48:63], v[252:255], v[92:95], v[48:63]
	s_waitcnt lgkmcnt(6)
	v_mfma_f32_32x32x16_bf16 v[32:47], v[240:243], v[80:83], v[32:47]
	ds_read_b64_tr_b16 v[80:81], v163 offset:0x400
	ds_read_b64_tr_b16 v[82:83], v163 offset:0xc00
	s_waitcnt lgkmcnt(6)
	v_mfma_f32_32x32x16_bf16 v[32:47], v[244:247], v[84:87], v[32:47]
	ds_read_b64_tr_b16 v[84:85], v163 offset:0x1400
	ds_read_b64_tr_b16 v[86:87], v163 offset:0x1c00
	s_waitcnt lgkmcnt(6)
	v_mfma_f32_32x32x16_bf16 v[32:47], v[248:251], v[88:91], v[32:47]
	ds_read_b64_tr_b16 v[88:89], v163 offset:0x2400
	ds_read_b64_tr_b16 v[90:91], v163 offset:0x2c00
	ds_read_b64_tr_b16 v[92:93], v163 offset:0x3400
	ds_read_b64_tr_b16 v[94:95], v163 offset:0x3c00
	s_waitcnt lgkmcnt(8)
	v_mfma_f32_32x32x16_bf16 v[32:47], v[252:255], v[228:231], v[32:47]
	s_waitcnt lgkmcnt(6)
	v_mfma_f32_32x32x16_bf16 v[16:31], v[240:243], v[80:83], v[16:31]
	ds_read_b64_tr_b16 v[80:81], v163 offset:0x600
	ds_read_b64_tr_b16 v[82:83], v163 offset:0xe00
	s_waitcnt lgkmcnt(6)
	v_mfma_f32_32x32x16_bf16 v[16:31], v[244:247], v[84:87], v[16:31]
	ds_read_b64_tr_b16 v[84:85], v163 offset:0x1600
	ds_read_b64_tr_b16 v[86:87], v163 offset:0x1e00
	s_waitcnt lgkmcnt(6)
	v_mfma_f32_32x32x16_bf16 v[16:31], v[248:251], v[88:91], v[16:31]
	ds_read_b64_tr_b16 v[88:89], v163 offset:0x2600
	ds_read_b64_tr_b16 v[90:91], v163 offset:0x2e00
	ds_read_b64_tr_b16 v[228:229], v163 offset:0x3600
	ds_read_b64_tr_b16 v[230:231], v163 offset:0x3e00
	s_waitcnt lgkmcnt(8)
	v_mfma_f32_32x32x16_bf16 v[16:31], v[252:255], v[92:95], v[16:31]
	s_waitcnt lgkmcnt(6)
	v_mfma_f32_32x32x16_bf16 v[0:15], v[240:243], v[80:83], v[0:15]
	s_waitcnt lgkmcnt(4)
	v_mfma_f32_32x32x16_bf16 v[0:15], v[244:247], v[84:87], v[0:15]
	s_waitcnt lgkmcnt(2)
	v_mfma_f32_32x32x16_bf16 v[0:15], v[248:251], v[88:91], v[0:15]
	s_waitcnt lgkmcnt(0)
	v_mfma_f32_32x32x16_bf16 v[0:15], v[252:255], v[228:231], v[0:15]
	s_branch .LBB0_391
; #define SBAR() __builtin_amdgcn_sched_barrier(0)
; __device__ __forceinline__ int crow(int r, int hi) { return (r & 3) + 8 * (r >> 2) + 4 * hi; }
; template <int D0> __device__ __forceinline__ void pv_one(f32x16& od, int vb, bf16x8 pa0, bf16x8 pa1, bf16x8 pa2, bf16x8 pa3) {
;   const s16x4 l0 = tr_read<v_rd_off(D0, 0, 0)>(vb), h0 = tr_read<v_rd_off(D0, 0, 1)>(vb), l1 = tr_read<v_rd_off(D0, 1, 0)>(vb), h1 = tr_read<v_rd_off(D0, 1, 1)>(vb);
;   const s16x4 l2 = tr_read<v_rd_off(D0, 2, 0)>(vb), h2 = tr_read<v_rd_off(D0, 2, 1)>(vb), l3 = tr_read<v_rd_off(D0, 3, 0)>(vb), h3 = tr_read<v_rd_off(D0, 3, 1)>(vb);
;   asm volatile("s_waitcnt lgkmcnt(0)" ::: "memory"); SBAR();
;     ...
;   od = __builtin_amdgcn_mfma_f32_32x32x16_bf16(pa0, PK(l0, h0), od, 0, 0, 0);
;   od = __builtin_amdgcn_mfma_f32_32x32x16_bf16(pa1, PK(l1, h1), od, 0, 0, 0);
;   od = __builtin_amdgcn_mfma_f32_32x32x16_bf16(pa2, PK(l2, h2), od, 0, 0, 0);
;   od = __builtin_amdgcn_mfma_f32_32x32x16_bf16(pa3, PK(l3, h3), od, 0, 0, 0);
;     ...
; }
; __device__ __forceinline__ void pv_d0(f32x16* o, int vb, bf16x8 pa0, bf16x8 pa1, bf16x8 pa2, bf16x8 pa3) {
;   pv_one<0>(o[0], vb, pa0, pa1, pa2, pa3); pv_one<1>(o[1], vb, pa0, pa1, pa2, pa3); pv_one<2>(o[2], vb, pa0, pa1, pa2, pa3); pv_one<3>(o[3], vb, pa0, pa1, pa2, pa3);
; __device__ __forceinline__ void attn_core_pair(f32x16 (&o)[4], const bf16_t* __restrict__ Qb, const bf16_t* __restrict__ Kh, const bf16_t* __restrict__ Vh, const int seq, const float C, const float thr_raw, char* lds) {
;     ...
;       if (__builtin_amdgcn_readfirstlane(fl_l[pp * 4 + rb]) != 0u) {
;         const float* al = ma + 256 + pp * 128 + rb * 32;
; #pragma unroll
;         for (int d = 0; d < 4; ++d)
; #pragma unroll
;           for (int r = 0; r < 16; ++r) o[d][r] *= al[crow(r, hi)]; }
;       if (role != pp) { pa0 = *(const bf16x8*)(P_l); pa1 = *(const bf16x8*)(P_l + 1024); pa2 = *(const bf16x8*)(P_l + 2048); pa3 = *(const bf16x8*)(P_l + 3072); }
;       pv_d0(o, vb0 + vprev * (2 * SHM_V), pa0, pa1, pa2, pa3);
.Ldiff_cons:
	s_or_b64 exec, exec, s[30:31]
	v_lshl_add_u32 v80, s99, 4, v200
	ds_read_b32 v80, v80
	s_waitcnt lgkmcnt(0)
	v_readfirstlane_b32 s98, v80
	s_cmp_eq_u32 s98, 0
	s_cbranch_scc1 .Ldiff_c_nors
	v_lshl_add_u32 v92, s99, 9, v215
	ds_read_b128 v[80:83], v92 offset:96
	ds_read_b128 v[84:87], v92 offset:64
	ds_read_b128 v[88:91], v92 offset:32
	ds_read_b128 v[92:95], v92
	s_waitcnt lgkmcnt(3)
	v_pk_mul_f32 v[62:63], v[62:63], v[82:83]
	s_waitcnt lgkmcnt(2)
	v_pk_mul_f32 v[58:59], v[58:59], v[86:87]
	s_waitcnt lgkmcnt(1)
	v_pk_mul_f32 v[54:55], v[54:55], v[90:91]
	s_waitcnt lgkmcnt(0)
	v_pk_mul_f32 v[50:51], v[50:51], v[94:95]
	v_pk_mul_f32 v[60:61], v[60:61], v[80:81]
	v_pk_mul_f32 v[56:57], v[56:57], v[84:85]
	v_pk_mul_f32 v[52:53], v[52:53], v[88:89]
	v_pk_mul_f32 v[48:49], v[48:49], v[92:93]
	v_pk_mul_f32 v[46:47], v[82:83], v[46:47]
	v_pk_mul_f32 v[42:43], v[86:87], v[42:43]
	v_pk_mul_f32 v[38:39], v[90:91], v[38:39]
	v_pk_mul_f32 v[34:35], v[94:95], v[34:35]
	v_pk_mul_f32 v[44:45], v[80:81], v[44:45]
	v_pk_mul_f32 v[40:41], v[84:85], v[40:41]
	v_pk_mul_f32 v[36:37], v[88:89], v[36:37]
	v_pk_mul_f32 v[32:33], v[92:93], v[32:33]
	v_pk_mul_f32 v[30:31], v[82:83], v[30:31]
	v_pk_mul_f32 v[26:27], v[86:87], v[26:27]
	v_pk_mul_f32 v[22:23], v[90:91], v[22:23]
	v_pk_mul_f32 v[18:19], v[94:95], v[18:19]
	v_pk_mul_f32 v[28:29], v[80:81], v[28:29]
	v_pk_mul_f32 v[24:25], v[84:85], v[24:25]
	v_pk_mul_f32 v[20:21], v[88:89], v[20:21]
	v_pk_mul_f32 v[16:17], v[92:93], v[16:17]
	v_pk_mul_f32 v[14:15], v[82:83], v[14:15]
	v_pk_mul_f32 v[10:11], v[86:87], v[10:11]
	v_pk_mul_f32 v[6:7], v[90:91], v[6:7]
	v_pk_mul_f32 v[2:3], v[94:95], v[2:3]
	v_pk_mul_f32 v[12:13], v[80:81], v[12:13]
	v_pk_mul_f32 v[8:9], v[84:85], v[8:9]
	v_pk_mul_f32 v[4:5], v[88:89], v[4:5]
	v_pk_mul_f32 v[0:1], v[92:93], v[0:1]
.Ldiff_c_nors:
	v_lshl_add_u32 v163, s16, 15, v204
	ds_read_b64_tr_b16 v[80:81], v163 offset:0
	ds_read_b64_tr_b16 v[82:83], v163 offset:0x800
	ds_read_b64_tr_b16 v[84:85], v163 offset:0x1000
	ds_read_b64_tr_b16 v[86:87], v163 offset:0x1800
	ds_read_b64_tr_b16 v[88:89], v163 offset:0x2000
	ds_read_b64_tr_b16 v[90:91], v163 offset:0x2800
	ds_read_b64_tr_b16 v[92:93], v163 offset:0x3000
	ds_read_b64_tr_b16 v[94:95], v163 offset:0x3800
	s_waitcnt lgkmcnt(6)
	v_mfma_f32_32x32x16_bf16 v[48:63], v[64:67], v[80:83], v[48:63]
	ds_read_b64_tr_b16 v[80:81], v163 offset:0x200
	ds_read_b64_tr_b16 v[82:83], v163 offset:0xa00
	s_waitcnt lgkmcnt(6)
	v_mfma_f32_32x32x16_bf16 v[48:63], v[68:71], v[84:87], v[48:63]
	ds_read_b64_tr_b16 v[84:85], v163 offset:0x1200
	ds_read_b64_tr_b16 v[86:87], v163 offset:0x1a00
	s_waitcnt lgkmcnt(6)
	v_mfma_f32_32x32x16_bf16 v[48:63], v[76:79], v[88:91], v[48:63]
	ds_read_b64_tr_b16 v[88:89], v163 offset:0x2200
	ds_read_b64_tr_b16 v[90:91], v163 offset:0x2a00
	ds_read_b64_tr_b16 v[228:229], v163 offset:0x3200
	ds_read_b64_tr_b16 v[230:231], v163 offset:0x3a00
	s_waitcnt lgkmcnt(8)
	v_mfma_f32_32x32x16_bf16 v[48:63], v[72:75], v[92:95], v[48:63]
	s_waitcnt lgkmcnt(6)
	v_mfma_f32_32x32x16_bf16 v[32:47], v[64:67], v[80:83], v[32:47]
	ds_read_b64_tr_b16 v[80:81], v163 offset:0x400
	ds_read_b64_tr_b16 v[82:83], v163 offset:0xc00
	s_waitcnt lgkmcnt(6)
	v_mfma_f32_32x32x16_bf16 v[32:47], v[68:71], v[84:87], v[32:47]
	ds_read_b64_tr_b16 v[84:85], v163 offset:0x1400
	ds_read_b64_tr_b16 v[86:87], v163 offset:0x1c00
	s_waitcnt lgkmcnt(6)
	v_mfma_f32_32x32x16_bf16 v[32:47], v[76:79], v[88:91], v[32:47]
	ds_read_b64_tr_b16 v[88:89], v163 offset:0x2400
	ds_read_b64_tr_b16 v[90:91], v163 offset:0x2c00
	ds_read_b64_tr_b16 v[92:93], v163 offset:0x3400
	ds_read_b64_tr_b16 v[94:95], v163 offset:0x3c00
	s_waitcnt lgkmcnt(8)
	v_mfma_f32_32x32x16_bf16 v[32:47], v[72:75], v[228:231], v[32:47]
	s_waitcnt lgkmcnt(6)
	v_mfma_f32_32x32x16_bf16 v[16:31], v[64:67], v[80:83], v[16:31]
	ds_read_b64_tr_b16 v[80:81], v163 offset:0x600
	ds_read_b64_tr_b16 v[82:83], v163 offset:0xe00
	s_waitcnt lgkmcnt(6)
	v_mfma_f32_32x32x16_bf16 v[16:31], v[68:71], v[84:87], v[16:31]
	ds_read_b64_tr_b16 v[84:85], v163 offset:0x1600
	ds_read_b64_tr_b16 v[86:87], v163 offset:0x1e00
	s_waitcnt lgkmcnt(6)
	v_mfma_f32_32x32x16_bf16 v[16:31], v[76:79], v[88:91], v[16:31]
	ds_read_b64_tr_b16 v[88:89], v163 offset:0x2600
	ds_read_b64_tr_b16 v[90:91], v163 offset:0x2e00
	ds_read_b64_tr_b16 v[228:229], v163 offset:0x3600
	ds_read_b64_tr_b16 v[230:231], v163 offset:0x3e00
	s_waitcnt lgkmcnt(8)
	v_mfma_f32_32x32x16_bf16 v[16:31], v[72:75], v[92:95], v[16:31]
	s_waitcnt lgkmcnt(6)
	v_mfma_f32_32x32x16_bf16 v[0:15], v[64:67], v[80:83], v[0:15]
	s_waitcnt lgkmcnt(4)
	v_mfma_f32_32x32x16_bf16 v[0:15], v[68:71], v[84:87], v[0:15]
	s_waitcnt lgkmcnt(2)
	v_mfma_f32_32x32x16_bf16 v[0:15], v[76:79], v[88:91], v[0:15]
	s_waitcnt lgkmcnt(0)
	v_mfma_f32_32x32x16_bf16 v[0:15], v[72:75], v[228:231], v[0:15]

; __global__ void __launch_bounds__(512, 2) fwd_megakernel(const Params p) {
	.amdhsa_kernel _Z14fwd_megakernel6Params
		.amdhsa_group_segment_fixed_size 0
		.amdhsa_private_segment_fixed_size 0
		.amdhsa_kernarg_size 488
		.amdhsa_user_sgpr_count 2
		.amdhsa_user_sgpr_dispatch_ptr 0
		.amdhsa_user_sgpr_queue_ptr 0
		.amdhsa_user_sgpr_kernarg_segment_ptr 1
		.amdhsa_user_sgpr_dispatch_id 0
		.amdhsa_user_sgpr_kernarg_preload_length 0
		.amdhsa_user_sgpr_kernarg_preload_offset 0
		.amdhsa_user_sgpr_private_segment_size 0
		.amdhsa_uses_dynamic_stack 0
		.amdhsa_enable_private_segment 0
		.amdhsa_system_sgpr_workgroup_id_x 1
		.amdhsa_system_sgpr_workgroup_id_y 0
		.amdhsa_system_sgpr_workgroup_id_z 0
		.amdhsa_system_sgpr_workgroup_info 0
		.amdhsa_system_vgpr_workitem_id 2
		.amdhsa_next_free_vgpr 256
		.amdhsa_next_free_sgpr 102
		.amdhsa_accum_offset 256
		.amdhsa_reserve_vcc 1
		.amdhsa_float_round_mode_32 0
		.amdhsa_float_round_mode_16_64 0
		.amdhsa_float_denorm_mode_32 3
		.amdhsa_float_denorm_mode_16_64 3
		.amdhsa_dx10_clamp 1
		.amdhsa_ieee_mode 1
		.amdhsa_fp16_overflow 0
		.amdhsa_tg_split 0
		.amdhsa_exception_fp_ieee_invalid_op 0
		.amdhsa_exception_fp_denorm_src 0
		.amdhsa_exception_fp_ieee_div_zero 0
		.amdhsa_exception_fp_ieee_overflow 0
		.amdhsa_exception_fp_ieee_underflow 0
		.amdhsa_exception_fp_ieee_inexact 0
		.amdhsa_exception_int_div_zero 0
	.end_amdhsa_kernel

; __global__ void __launch_bounds__(512, 2) fwd_megakernel(const Params p) {
amdhsa.kernels:
  - .agpr_count:     0
    .args:
      - .offset:         0
        .size:           232
        .value_kind:     by_value
      - .offset:         232
        .size:           4
        .value_kind:     hidden_block_count_x
      - .offset:         236
        .size:           4
        .value_kind:     hidden_block_count_y
      - .offset:         240
        .size:           4
        .value_kind:     hidden_block_count_z
      - .offset:         244
        .size:           2
        .value_kind:     hidden_group_size_x
      - .offset:         246
        .size:           2
        .value_kind:     hidden_group_size_y
      - .offset:         248
        .size:           2
        .value_kind:     hidden_group_size_z
      - .offset:         250
        .size:           2
        .value_kind:     hidden_remainder_x
      - .offset:         252
        .size:           2
        .value_kind:     hidden_remainder_y
      - .offset:         254
        .size:           2
        .value_kind:     hidden_remainder_z
      - .offset:         272
        .size:           8
        .value_kind:     hidden_global_offset_x
      - .offset:         280
        .size:           8
        .value_kind:     hidden_global_offset_y
      - .offset:         288
        .size:           8
        .value_kind:     hidden_global_offset_z
      - .offset:         296
        .size:           2
        .value_kind:     hidden_grid_dims
      - .offset:         320
        .size:           8
        .value_kind:     hidden_multigrid_sync_arg
      - .offset:         352
        .size:           4
        .value_kind:     hidden_dynamic_lds_size
    .group_segment_fixed_size: 0
    .kernarg_segment_align: 8
    .kernarg_segment_size: 488
    .language:       OpenCL C
    .language_version:
      - 2
      - 0
    .max_flat_workgroup_size: 512
    .name:           _Z14fwd_megakernel6Params
    .private_segment_fixed_size: 0
    .sgpr_count:     108
    .sgpr_spill_count: 1
    .symbol:         _Z14fwd_megakernel6Params.kd
    .uniform_work_group_size: 1
    .uses_dynamic_stack: false
    .vgpr_count:     256
    .vgpr_spill_count: 0
    .wavefront_size: 64
